# PEER U pass: both prefetch load bursts spread through the compute blocks (unconditional last prefetch, drained at exit)
# speedup vs baseline: 1.0331x; 1.0060x over previous
.LBB0_924:
	s_add_i32 s15, s61, 0xffffff80
	s_and_b32 s65, s15, 0x780
	s_add_i32 s14, s59, 0xfffc0000
	s_add_i32 s1, s0, 1
	s_and_b32 s14, s14, 0x1e00000
	s_add_u32 s14, s36, s14
	s_addc_u32 s15, s37, 0
	s_add_i32 s34, s63, -16
	s_and_b32 s34, s34, 0x780
	v_lshl_add_u32 v80, s65, 2, v189
	ds_read_b128 v[68:71], v80
	ds_read_b128 v[72:75], v80 offset:16
	ds_read_b128 v[76:79], v80 offset:32
	ds_read_b128 v[80:83], v80 offset:48
	s_waitcnt lgkmcnt(0)
	v_mov_b32_e32 v138, v139
	v_mov_b32_e32 v178, v139
	v_mov_b32_e32 v185, v139
	v_mov_b32_e32 v186, v139
	s_waitcnt vmcnt(0)
	v_dot4c_i32_i8_e32 v138, v0, v64
	v_dot4c_i32_i8_e32 v178, v4, v64
	v_dot4c_i32_i8_e32 v185, v32, v64
	v_dot4c_i32_i8_e32 v186, v36, v64
	v_dot4c_i32_i8_e32 v138, v1, v65
	v_lshlrev_b32_e32 v69, 7, v69
	v_lshlrev_b32_e32 v68, 7, v68
	v_or_b32_e32 v69, v69, v137
	v_or_b32_e32 v68, v68, v174
	global_load_dwordx4 v[132:135], v68, s[14:15]
	global_load_dwordx4 v[128:131], v69, s[14:15]
	v_dot4c_i32_i8_e32 v178, v5, v65
	v_dot4c_i32_i8_e32 v185, v33, v65
	v_dot4c_i32_i8_e32 v186, v37, v65
	v_dot4c_i32_i8_e32 v138, v2, v66
	v_dot4c_i32_i8_e32 v178, v6, v66
	v_dot4c_i32_i8_e32 v185, v34, v66
	v_dot4c_i32_i8_e32 v186, v38, v66
	v_dot4c_i32_i8_e32 v138, v3, v67
	v_dot4c_i32_i8_e32 v178, v7, v67
	v_dot4c_i32_i8_e32 v185, v35, v67
	v_dot4c_i32_i8_e32 v186, v39, v67
	v_mov_b32_e32 v180, v139
	v_lshlrev_b32_e32 v69, 7, v70
	v_lshlrev_b32_e32 v68, 7, v71
	v_or_b32_e32 v69, v69, v174
	v_or_b32_e32 v68, v68, v137
	global_load_dwordx4 v[124:127], v69, s[14:15]
	global_load_dwordx4 v[120:123], v68, s[14:15]
	v_mov_b32_e32 v210, v139
	v_cndmask_b32_e64 v215, v185, v138, s[2:3]
	v_cndmask_b32_e64 v138, v138, v185, s[2:3]
	v_cndmask_b32_e64 v185, v178, v186, s[2:3]
	ds_bpermute_b32 v185, v201, v185
	v_dot4c_i32_i8_e32 v180, v12, v64
	v_mov_b32_e32 v181, v139
	v_dot4c_i32_i8_e32 v210, v44, v64
	v_mov_b32_e32 v211, v139
	v_dot4c_i32_i8_e32 v180, v13, v65
	v_dot4c_i32_i8_e32 v181, v16, v64
	v_lshlrev_b32_e32 v69, 7, v72
	v_lshlrev_b32_e32 v68, 7, v73
	v_or_b32_e32 v69, v69, v174
	v_or_b32_e32 v68, v68, v137
	global_load_dwordx4 v[116:119], v69, s[14:15]
	global_load_dwordx4 v[112:115], v68, s[14:15]
	v_dot4c_i32_i8_e32 v210, v45, v65
	v_dot4c_i32_i8_e32 v211, v48, v64
	v_dot4c_i32_i8_e32 v180, v14, v66
	v_dot4c_i32_i8_e32 v181, v17, v65
	v_dot4c_i32_i8_e32 v210, v46, v66
	v_dot4c_i32_i8_e32 v211, v49, v65
	v_dot4c_i32_i8_e32 v180, v15, v67
	v_dot4c_i32_i8_e32 v181, v18, v66
	v_dot4c_i32_i8_e32 v210, v47, v67
	v_dot4c_i32_i8_e32 v211, v50, v66
	v_cndmask_b32_e64 v178, v186, v178, s[2:3]
	v_lshlrev_b32_e32 v69, 7, v74
	v_lshlrev_b32_e32 v68, 7, v75
	v_or_b32_e32 v69, v69, v174
	v_or_b32_e32 v68, v68, v137
	global_load_dwordx4 v[108:111], v69, s[14:15]
	global_load_dwordx4 v[104:107], v68, s[14:15]
	v_mov_b32_e32 v179, v139
	v_dot4c_i32_i8_e32 v181, v19, v67
	v_mov_b32_e32 v182, v139
	v_mov_b32_e32 v187, v139
	v_dot4c_i32_i8_e32 v211, v51, v67
	v_mov_b32_e32 v212, v139
	s_waitcnt lgkmcnt(0)
	v_add_u32_e32 v178, v185, v178
	v_cndmask_b32_e64 v185, v210, v180, s[2:3]
	v_cndmask_b32_e64 v180, v180, v210, s[2:3]
	v_dot4c_i32_i8_e32 v179, v8, v64
	v_dot4c_i32_i8_e32 v182, v20, v64
	v_lshlrev_b32_e32 v69, 7, v76
	v_lshlrev_b32_e32 v68, 7, v77
	v_or_b32_e32 v69, v69, v174
	v_or_b32_e32 v68, v68, v137
	global_load_dwordx4 v[100:103], v69, s[14:15]
	global_load_dwordx4 v[96:99], v68, s[14:15]
	v_mov_b32_e32 v183, v139
	v_dot4c_i32_i8_e32 v187, v40, v64
	v_dot4c_i32_i8_e32 v212, v52, v64
	v_mov_b32_e32 v213, v139
	ds_bpermute_b32 v180, v201, v180
	v_cndmask_b32_e64 v186, v181, v211, s[2:3]
	v_dot4c_i32_i8_e32 v179, v9, v65
	v_dot4c_i32_i8_e32 v182, v21, v65
	v_dot4c_i32_i8_e32 v183, v24, v64
	v_mov_b32_e32 v184, v139
	v_dot4c_i32_i8_e32 v187, v41, v65
	v_lshlrev_b32_e32 v69, 7, v78
	v_lshlrev_b32_e32 v68, 7, v79
	v_or_b32_e32 v69, v69, v174
	v_or_b32_e32 v68, v68, v137
	global_load_dwordx4 v[92:95], v69, s[14:15]
	global_load_dwordx4 v[88:91], v68, s[14:15]
	v_dot4c_i32_i8_e32 v212, v53, v65
	v_dot4c_i32_i8_e32 v213, v56, v64
	v_mov_b32_e32 v214, v139
	ds_bpermute_b32 v186, v201, v186
	v_dot4c_i32_i8_e32 v179, v10, v66
	v_dot4c_i32_i8_e32 v182, v22, v66
	v_dot4c_i32_i8_e32 v183, v25, v65
	v_dot4c_i32_i8_e32 v184, v28, v64
	v_dot4c_i32_i8_e32 v187, v42, v66
	v_dot4c_i32_i8_e32 v212, v54, v66
	v_dot4c_i32_i8_e32 v213, v57, v65
	v_lshlrev_b32_e32 v69, 7, v80
	v_and_or_b32 v80, s1, 15, v176
	v_lshlrev_b32_e32 v68, 7, v81
	v_ashrrev_i32_e32 v81, 31, v80
	v_lshlrev_b64 v[80:81], 11, v[80:81]
	v_or_b32_e32 v68, v68, v137
	v_or_b32_e32 v69, v69, v174
	v_lshl_add_u64 v[80:81], s[30:31], 0, v[80:81]
	global_load_dwordx4 v[84:87], v69, s[14:15]
	global_load_dwordx4 v[76:79], v68, s[14:15]
	v_dot4c_i32_i8_e32 v214, v60, v64
	v_dot4c_i32_i8_e32 v179, v11, v67
	v_dot4c_i32_i8_e32 v182, v23, v67
	v_dot4c_i32_i8_e32 v183, v26, v66
	v_dot4c_i32_i8_e32 v184, v29, v65
	v_dot4c_i32_i8_e32 v187, v43, v67
	v_dot4c_i32_i8_e32 v212, v55, v67
	v_dot4c_i32_i8_e32 v213, v58, v66
	v_dot4c_i32_i8_e32 v214, v61, v65
	v_dot4c_i32_i8_e32 v183, v27, v67
	v_dot4c_i32_i8_e32 v184, v30, v66
	v_dot4c_i32_i8_e32 v213, v59, v67
	v_lshlrev_b32_e32 v68, 7, v83
	v_lshlrev_b32_e32 v69, 7, v82
	v_lshl_add_u64 v[80:81], v[80:81], 0, s[34:35]
	v_or_b32_e32 v68, v68, v137
	v_or_b32_e32 v69, v69, v174
	v_lshl_add_u64 v[80:81], v[80:81], 0, v[142:143]
	global_load_dwordx4 v[72:75], v69, s[14:15]
	global_load_dwordx4 v[68:71], v68, s[14:15]
	global_load_dwordx4 v[80:83], v[80:81], off
	v_dot4c_i32_i8_e32 v214, v62, v66
	v_cndmask_b32_e64 v216, v179, v187, s[2:3]
	v_cndmask_b32_e64 v179, v187, v179, s[2:3]
	v_cndmask_b32_e64 v187, v182, v212, s[2:3]
	v_dot4c_i32_i8_e32 v184, v31, v67
	v_dot4c_i32_i8_e32 v214, v63, v67
	ds_bpermute_b32 v138, v201, v138
	ds_bpermute_b32 v187, v201, v187
	s_waitcnt lgkmcnt(3)
	v_add_u32_e32 v180, v180, v185
	v_cndmask_b32_e64 v181, v211, v181, s[2:3]
	v_cndmask_b32_e64 v185, v213, v183, s[2:3]
	v_cndmask_b32_e64 v183, v183, v213, s[2:3]
	ds_bpermute_b32 v216, v201, v216
	s_waitcnt lgkmcnt(3)
	v_add_u32_e32 v181, v186, v181
	ds_bpermute_b32 v183, v201, v183
	v_cndmask_b32_e64 v186, v184, v214, s[2:3]
	ds_bpermute_b32 v186, v201, v186
	v_cndmask_b32_e64 v182, v212, v182, s[2:3]
	s_waitcnt lgkmcnt(4)
	v_add_u32_e32 v138, v138, v215
	s_waitcnt lgkmcnt(3)
	v_add_u32_e32 v182, v187, v182
	s_waitcnt lgkmcnt(2)
	v_add_u32_e32 v179, v216, v179
	v_cndmask_b32_e64 v187, v138, v181, s[4:5]
	s_waitcnt lgkmcnt(1)
	v_add_u32_e32 v183, v183, v185
	v_cndmask_b32_e64 v184, v214, v184, s[2:3]
	v_cndmask_b32_e64 v138, v181, v138, s[4:5]
	v_cndmask_b32_e64 v181, v182, v178, s[4:5]
	v_cndmask_b32_e64 v178, v178, v182, s[4:5]
	s_waitcnt lgkmcnt(0)
	v_add_u32_e32 v184, v186, v184
	ds_bpermute_b32 v178, v202, v178
	v_cndmask_b32_e64 v182, v179, v183, s[4:5]
	ds_bpermute_b32 v187, v202, v187
	ds_bpermute_b32 v182, v202, v182
	v_cndmask_b32_e64 v185, v180, v184, s[4:5]
	ds_bpermute_b32 v185, v202, v185
	s_waitcnt lgkmcnt(3)
	v_add_u32_e32 v181, v178, v181
	v_cndmask_b32_e64 v178, v183, v179, s[4:5]
	s_waitcnt lgkmcnt(2)
	v_add_u32_e32 v138, v187, v138
	s_waitcnt lgkmcnt(1)
	v_add_u32_e32 v178, v182, v178
	v_cndmask_b32_e64 v179, v184, v180, s[4:5]
	s_waitcnt lgkmcnt(0)
	v_add_u32_e32 v179, v185, v179
	v_cndmask_b32_e64 v180, v138, v178, s[6:7]
	ds_bpermute_b32 v180, v203, v180
	v_cndmask_b32_e64 v182, v181, v179, s[6:7]
	ds_bpermute_b32 v182, v203, v182
	s_add_i32 s1, s61, 0xffffff00
	v_cndmask_b32_e64 v138, v178, v138, s[6:7]
	s_and_b32 s1, s1, 0x700
	s_waitcnt lgkmcnt(1)
	v_add_u32_e32 v178, v180, v138
	v_cndmask_b32_e64 v138, v179, v181, s[6:7]
	s_cmp_gt_u32 s0, 15
	s_waitcnt lgkmcnt(0)
	v_add_u32_e32 v179, v182, v138
	s_cselect_b64 s[14:15], -1, 0
	s_cmp_lt_u32 s0, 16
	v_lshl_add_u32 v138, s1, 2, v190
	s_cbranch_scc1 .LBB0_926
	ds_read_b64 v[180:181], v138
	s_waitcnt lgkmcnt(0)
	v_add_u32_e32 v178, v180, v178
	v_add_u32_e32 v179, v181, v179
.LBB0_926:
	s_add_i32 s67, s0, 2
	s_cmpk_gt_u32 s0, 0xfd
	s_cselect_b64 s[0:1], -1, 0
	s_and_b64 vcc, exec, s[0:1]
	ds_write_b64 v138, v[178:179]
	s_and_b32 s17, s61, 0x700
	v_lshl_add_u32 v0, s17, 2, v189
	ds_read_b128 v[6:9], v0
	ds_read_b128 v[22:25], v0 offset:16
	ds_read_b128 v[38:41], v0 offset:32
	ds_read_b128 v[54:57], v0 offset:48
	v_and_or_b32 v64, s67, 14, v176
	s_and_b32 s16, s59, 0x3e00000
	v_ashrrev_i32_e32 v65, 31, v64
	s_add_u32 s16, s36, s16
	v_lshlrev_b64 v[64:65], 11, v[64:65]
	s_addc_u32 s17, s37, 0
	v_lshl_add_u64 v[64:65], s[30:31], 0, v[64:65]
	s_and_b32 s34, s63, 0xf80
	s_waitcnt lgkmcnt(3)
	v_lshlrev_b32_e32 v0, 7, v7
	v_lshlrev_b32_e32 v1, 7, v6
	v_lshlrev_b32_e32 v9, 7, v9
	v_lshlrev_b32_e32 v8, 7, v8
	s_waitcnt lgkmcnt(2)
	v_lshlrev_b32_e32 v16, 7, v23
	v_lshlrev_b32_e32 v17, 7, v22
	v_lshlrev_b32_e32 v25, 7, v25
	v_lshlrev_b32_e32 v24, 7, v24
	s_waitcnt lgkmcnt(1)
	v_lshlrev_b32_e32 v32, 7, v39
	v_lshlrev_b32_e32 v33, 7, v38
	v_lshlrev_b32_e32 v41, 7, v41
	v_lshlrev_b32_e32 v40, 7, v40
	s_waitcnt lgkmcnt(0)
	v_lshlrev_b32_e32 v48, 7, v55
	v_lshlrev_b32_e32 v49, 7, v54
	v_lshlrev_b32_e32 v57, 7, v57
	v_lshlrev_b32_e32 v56, 7, v56
	v_lshl_add_u64 v[64:65], v[64:65], 0, s[34:35]
	v_or_b32_e32 v4, v0, v137
	v_or_b32_e32 v0, v1, v174
	v_or_b32_e32 v12, v9, v137
	v_or_b32_e32 v8, v8, v174
	v_or_b32_e32 v20, v16, v137
	v_or_b32_e32 v16, v17, v174
	v_or_b32_e32 v28, v25, v137
	v_or_b32_e32 v24, v24, v174
	v_or_b32_e32 v36, v32, v137
	v_or_b32_e32 v32, v33, v174
	v_or_b32_e32 v44, v41, v137
	v_or_b32_e32 v40, v40, v174
	v_or_b32_e32 v52, v48, v137
	v_or_b32_e32 v48, v49, v174
	v_or_b32_e32 v60, v57, v137
	v_or_b32_e32 v56, v56, v174
	v_lshl_add_u64 v[64:65], v[64:65], 0, v[142:143]
.LBB0_928:
	v_mov_b32_e32 v138, v139
	s_waitcnt vmcnt(0)
	v_dot4c_i32_i8_e32 v138, v132, v80
	v_mov_b32_e32 v132, v139
	global_load_dwordx4 v[0:3], v0, s[16:17]
	v_dot4c_i32_i8_e32 v132, v128, v80
	v_mov_b32_e32 v128, v139
	v_dot4c_i32_i8_e32 v128, v124, v80
	v_mov_b32_e32 v124, v139
	v_dot4c_i32_i8_e32 v124, v120, v80
	global_load_dwordx4 v[4:7], v4, s[16:17]
	v_mov_b32_e32 v120, v139
	v_dot4c_i32_i8_e32 v120, v116, v80
	v_mov_b32_e32 v116, v139
	v_dot4c_i32_i8_e32 v116, v112, v80
	v_mov_b32_e32 v112, v139
	global_load_dwordx4 v[8:11], v8, s[16:17]
	v_dot4c_i32_i8_e32 v112, v108, v80
	v_mov_b32_e32 v108, v139
	v_dot4c_i32_i8_e32 v108, v104, v80
	v_mov_b32_e32 v104, v139
	v_dot4c_i32_i8_e32 v104, v100, v80
	global_load_dwordx4 v[12:15], v12, s[16:17]
	v_mov_b32_e32 v100, v139
	v_dot4c_i32_i8_e32 v100, v96, v80
	v_mov_b32_e32 v96, v139
	v_dot4c_i32_i8_e32 v96, v92, v80
	v_mov_b32_e32 v92, v139
	v_dot4c_i32_i8_e32 v92, v88, v80
	global_load_dwordx4 v[16:19], v16, s[16:17]
	v_mov_b32_e32 v88, v139
	v_dot4c_i32_i8_e32 v88, v84, v80
	v_mov_b32_e32 v84, v139
	v_dot4c_i32_i8_e32 v138, v133, v81
	v_dot4c_i32_i8_e32 v104, v101, v81
	global_load_dwordx4 v[20:23], v20, s[16:17]
	v_dot4c_i32_i8_e32 v84, v76, v80
	v_mov_b32_e32 v76, v139
	v_dot4c_i32_i8_e32 v138, v134, v82
	v_dot4c_i32_i8_e32 v132, v129, v81
	v_dot4c_i32_i8_e32 v104, v102, v82
	global_load_dwordx4 v[24:27], v24, s[16:17]
	v_dot4c_i32_i8_e32 v100, v97, v81
	v_dot4c_i32_i8_e32 v76, v72, v80
	v_mov_b32_e32 v72, v139
	v_dot4c_i32_i8_e32 v138, v135, v83
	v_dot4c_i32_i8_e32 v132, v130, v82
	global_load_dwordx4 v[28:31], v28, s[16:17]
	v_dot4c_i32_i8_e32 v128, v125, v81
	v_dot4c_i32_i8_e32 v104, v103, v83
	v_dot4c_i32_i8_e32 v100, v98, v82
	v_dot4c_i32_i8_e32 v96, v93, v81
	v_dot4c_i32_i8_e32 v72, v68, v80
	global_load_dwordx4 v[32:35], v32, s[16:17]
	v_dot4c_i32_i8_e32 v132, v131, v83
	v_dot4c_i32_i8_e32 v128, v126, v82
	v_dot4c_i32_i8_e32 v124, v121, v81
	v_dot4c_i32_i8_e32 v100, v99, v83
	v_dot4c_i32_i8_e32 v96, v94, v82
	global_load_dwordx4 v[36:39], v36, s[16:17]
	v_dot4c_i32_i8_e32 v92, v89, v81
	v_dot4c_i32_i8_e32 v72, v69, v81
	v_cndmask_b32_e64 v69, v138, v104, s[2:3]
	v_dot4c_i32_i8_e32 v128, v127, v83
	v_dot4c_i32_i8_e32 v124, v122, v82
	global_load_dwordx4 v[40:43], v40, s[16:17]
	v_dot4c_i32_i8_e32 v120, v117, v81
	v_dot4c_i32_i8_e32 v96, v95, v83
	v_dot4c_i32_i8_e32 v92, v90, v82
	v_dot4c_i32_i8_e32 v88, v85, v81
	v_dot4c_i32_i8_e32 v72, v70, v82
	global_load_dwordx4 v[44:47], v44, s[16:17]
	ds_bpermute_b32 v69, v201, v69
	v_cndmask_b32_e64 v70, v132, v100, s[2:3]
	v_dot4c_i32_i8_e32 v124, v123, v83
	v_dot4c_i32_i8_e32 v120, v118, v82
	v_dot4c_i32_i8_e32 v116, v113, v81
	global_load_dwordx4 v[48:51], v48, s[16:17]
	v_dot4c_i32_i8_e32 v92, v91, v83
	v_dot4c_i32_i8_e32 v88, v86, v82
	v_dot4c_i32_i8_e32 v84, v77, v81
	v_dot4c_i32_i8_e32 v72, v71, v83
	ds_bpermute_b32 v70, v201, v70
	v_cndmask_b32_e64 v71, v128, v96, s[2:3]
	global_load_dwordx4 v[52:55], v52, s[16:17]
	v_dot4c_i32_i8_e32 v120, v119, v83
	v_dot4c_i32_i8_e32 v116, v114, v82
	v_dot4c_i32_i8_e32 v88, v87, v83
	v_dot4c_i32_i8_e32 v84, v78, v82
	v_dot4c_i32_i8_e32 v76, v73, v81
	global_load_dwordx4 v[56:59], v56, s[16:17]
	ds_bpermute_b32 v71, v201, v71
	v_cndmask_b32_e64 v73, v124, v92, s[2:3]
	v_dot4c_i32_i8_e32 v116, v115, v83
	v_dot4c_i32_i8_e32 v84, v79, v83
	v_dot4c_i32_i8_e32 v76, v74, v82
	global_load_dwordx4 v[60:63], v60, s[16:17]
	ds_bpermute_b32 v73, v201, v73
	v_cndmask_b32_e64 v74, v120, v88, s[2:3]
	v_dot4c_i32_i8_e32 v76, v75, v83
	v_cndmask_b32_e64 v68, v104, v138, s[2:3]
	ds_bpermute_b32 v74, v201, v74
	global_load_dwordx4 v[64:67], v[64:65], off
	v_cndmask_b32_e64 v75, v116, v84, s[2:3]
	s_waitcnt lgkmcnt(4)
	v_add_u32_e32 v68, v69, v68
	v_cndmask_b32_e64 v69, v100, v132, s[2:3]
	ds_bpermute_b32 v75, v201, v75
	s_waitcnt lgkmcnt(4)
	v_add_u32_e32 v69, v70, v69
	v_cndmask_b32_e64 v70, v96, v128, s[2:3]
	v_dot4c_i32_i8_e32 v112, v109, v81
	v_dot4c_i32_i8_e32 v108, v105, v81
	s_waitcnt lgkmcnt(3)
	v_add_u32_e32 v70, v71, v70
	v_cndmask_b32_e64 v71, v92, v124, s[2:3]
	v_dot4c_i32_i8_e32 v112, v110, v82
	v_dot4c_i32_i8_e32 v108, v106, v82
	s_waitcnt lgkmcnt(2)
	v_add_u32_e32 v71, v73, v71
	v_cndmask_b32_e64 v73, v88, v120, s[2:3]
	v_dot4c_i32_i8_e32 v112, v111, v83
	v_dot4c_i32_i8_e32 v108, v107, v83
	s_waitcnt lgkmcnt(1)
	v_add_u32_e32 v73, v74, v73
	v_cndmask_b32_e64 v74, v84, v116, s[2:3]
	s_waitcnt lgkmcnt(0)
	v_add_u32_e32 v74, v75, v74
	v_cndmask_b32_e64 v75, v76, v112, s[2:3]
	v_cndmask_b32_e64 v76, v112, v76, s[2:3]
	v_cndmask_b32_e64 v77, v108, v72, s[2:3]
	ds_bpermute_b32 v76, v201, v76
	ds_bpermute_b32 v77, v201, v77
	v_cndmask_b32_e64 v72, v72, v108, s[2:3]
	v_cndmask_b32_e64 v78, v68, v73, s[4:5]
	v_cndmask_b32_e64 v68, v73, v68, s[4:5]
	s_waitcnt lgkmcnt(1)
	v_add_u32_e32 v75, v76, v75
	s_waitcnt lgkmcnt(0)
	v_add_u32_e32 v72, v77, v72
	v_cndmask_b32_e64 v73, v74, v69, s[4:5]
	v_cndmask_b32_e64 v69, v69, v74, s[4:5]
	v_cndmask_b32_e64 v74, v70, v75, s[4:5]
	v_cndmask_b32_e64 v76, v71, v72, s[4:5]
	ds_bpermute_b32 v78, v202, v78
	ds_bpermute_b32 v69, v202, v69
	ds_bpermute_b32 v74, v202, v74
	ds_bpermute_b32 v76, v202, v76
	v_cndmask_b32_e64 v70, v75, v70, s[4:5]
	v_cndmask_b32_e64 v71, v72, v71, s[4:5]
	s_waitcnt lgkmcnt(3)
	v_add_u32_e32 v68, v78, v68
	s_waitcnt lgkmcnt(2)
	v_add_u32_e32 v69, v69, v73
	s_waitcnt lgkmcnt(1)
	v_add_u32_e32 v70, v74, v70
	s_waitcnt lgkmcnt(0)
	v_add_u32_e32 v71, v76, v71
	v_cndmask_b32_e64 v72, v68, v70, s[6:7]
	v_cndmask_b32_e64 v73, v69, v71, s[6:7]
	ds_bpermute_b32 v72, v203, v72
	ds_bpermute_b32 v73, v203, v73
	v_cndmask_b32_e64 v68, v70, v68, s[6:7]
	v_cndmask_b32_e64 v69, v71, v69, s[6:7]
	s_andn2_b64 vcc, exec, s[14:15]
	s_waitcnt lgkmcnt(1)
	v_add_u32_e32 v68, v72, v68
	s_waitcnt lgkmcnt(0)
	v_add_u32_e32 v69, v73, v69
	v_lshl_add_u32 v70, s65, 2, v190
	s_cbranch_vccnz .LBB0_923
	ds_read_b64 v[72:73], v70
	s_waitcnt lgkmcnt(0)
	v_add_u32_e32 v68, v72, v68
	v_add_u32_e32 v69, v73, v69
	s_branch .LBB0_923
.LBB0_930:
	s_waitcnt vmcnt(0)
	v_mov_b32_e32 v0, v176
	v_mov_b32_e32 v1, v176
	s_mov_b32 s34, 1
	s_mov_b32 s59, 0
	s_mov_b32 s61, 16
